# out-projection epilogue stores (both layers) also written through (sc1)
# speedup vs baseline: 1.0122x; 1.0044x over previous
;     __device__ __forceinline__ void operator()(const f32x4 (&acc)[2][2][4][2], const pg8::Unit& u, int wr, int wc, int fr, int fq) const {
;     ...
;         const float* gp = gatev + (size_t)(u.pm >> 3) * 3072 + col0;
;         f32x4 gv[2][2];
; #pragma unroll
;         for (int bj = 0; bj < 2; ++bj)
; #pragma unroll
;             for (int n = 0; n < 2; ++n) gv[bj][n] = *(const f32x4*)(gp + bj * 128 + n * 16);
; #pragma unroll
;         for (int ai = 0; ai < 2; ++ai)
; #pragma unroll
;             for (int m = 0; m < 4; ++m) {
;                 const size_t off = (size_t)(row0 + ai * 128 + m * 16) * DM + col0;
; #pragma unroll
;                 for (int bj = 0; bj < 2; ++bj)
; #pragma unroll
;                     for (int n = 0; n < 2; ++n) {
;                         const f32x4 xv = *(const f32x4*)(xin + off + bj * 128 + n * 16);
;                         *(f32x4*)(out + off + bj * 128 + n * 16) = xv + gv[bj][n] * acc[ai][bj][m][n];
;                     }
;                 if (m == 3) asm volatile("" ::: "memory");
;             }
.LBB0_582:
	v_lshl_add_u32 v170, s30, 8, v158
	v_lshl_or_b32 v168, s56, 8, v160
	s_ashr_i32 s23, s30, 3
	v_ashrrev_i32_e32 v171, 31, v170
	s_mul_hi_i32 s25, s23, 0x3000
	s_mulk_i32 s23, 0x3000
	v_ashrrev_i32_e32 v169, 31, v168
	v_lshlrev_b64 v[130:131], 10, v[170:171]
	s_add_u32 s34, s49, s23
	v_lshl_add_u64 v[130:131], v[130:131], 0, v[168:169]
	s_addc_u32 s35, s50, s25
	v_lshlrev_b64 v[156:157], 2, v[130:131]
	v_lshl_add_u64 v[128:129], v[168:169], 2, s[34:35]
	v_and_b32_e32 v165, 0xffffff00, v170
	v_and_b32_e32 v166, 15, v170
	v_lshl_add_u32 v165, v166, 3, v165
	v_bfe_u32 v166, v170, 6, 1
	v_lshl_add_u32 v165, v166, 2, v165
	v_lshlrev_b32_e32 v165, 12, v165
	v_lshl_add_u32 v156, v168, 2, v165
	global_load_dwordx4 v[140:143], v[128:129], off
	global_load_dwordx4 v[136:139], v[128:129], off offset:64
	global_load_dwordx4 v[132:135], v[128:129], off offset:512
	s_nop 0
	global_load_dwordx4 v[128:131], v[128:129], off offset:576
	s_andn2_b64 vcc, exec, s[4:5]
	s_mov_b64 s[4:5], -1
	s_mov_b64 s[36:37], s[0:1]
	global_load_dwordx4 v[164:167], v156, s[36:37]
	global_load_dwordx4 v[168:171], v156, s[36:37] offset:64
	global_load_dwordx4 v[172:175], v156, s[36:37] offset:512
	global_load_dwordx4 v[176:179], v156, s[36:37] offset:576
	s_add_u32 s36, s0, 0x1000
	s_addc_u32 s37, s1, 0
	global_load_dwordx4 v[180:183], v156, s[36:37]
	global_load_dwordx4 v[184:187], v156, s[36:37] offset:64
	global_load_dwordx4 v[188:191], v156, s[36:37] offset:512
	global_load_dwordx4 v[192:195], v156, s[36:37] offset:576
	s_add_u32 s36, s0, 0x2000
	s_addc_u32 s37, s1, 0
	global_load_dwordx4 v[196:199], v156, s[36:37]
	global_load_dwordx4 v[204:207], v156, s[36:37] offset:64
	global_load_dwordx4 v[208:211], v156, s[36:37] offset:512
	global_load_dwordx4 v[212:215], v156, s[36:37] offset:576
	s_waitcnt vmcnt(8)
	v_pk_fma_f32 v[166:167], v[126:127], v[142:143], v[166:167]
	v_pk_fma_f32 v[164:165], v[124:125], v[140:141], v[164:165]
	v_pk_fma_f32 v[170:171], v[122:123], v[138:139], v[170:171]
	v_pk_fma_f32 v[168:169], v[120:121], v[136:137], v[168:169]
	v_pk_fma_f32 v[174:175], v[118:119], v[134:135], v[174:175]
	v_pk_fma_f32 v[172:173], v[116:117], v[132:133], v[172:173]
	v_pk_fma_f32 v[178:179], v[106:107], v[130:131], v[178:179]
	v_pk_fma_f32 v[176:177], v[104:105], v[128:129], v[176:177]
	s_mov_b64 s[38:39], s[8:9]
	global_store_dwordx4 v156, v[164:167], s[38:39] sc1
	global_store_dwordx4 v156, v[168:171], s[38:39] offset:64 sc1
	global_store_dwordx4 v156, v[172:175], s[38:39] offset:512 sc1
	global_store_dwordx4 v156, v[176:179], s[38:39] offset:576 sc1
	s_add_u32 s36, s0, 0x3000
	s_addc_u32 s37, s1, 0
	global_load_dwordx4 v[164:167], v156, s[36:37]
	global_load_dwordx4 v[168:171], v156, s[36:37] offset:64
	global_load_dwordx4 v[172:175], v156, s[36:37] offset:512
	global_load_dwordx4 v[176:179], v156, s[36:37] offset:576
	s_waitcnt vmcnt(12)
	v_pk_fma_f32 v[182:183], v[114:115], v[142:143], v[182:183]
	v_pk_fma_f32 v[180:181], v[112:113], v[140:141], v[180:181]
	v_pk_fma_f32 v[186:187], v[110:111], v[138:139], v[186:187]
	v_pk_fma_f32 v[184:185], v[108:109], v[136:137], v[184:185]
	v_pk_fma_f32 v[190:191], v[102:103], v[134:135], v[190:191]
	v_pk_fma_f32 v[188:189], v[100:101], v[132:133], v[188:189]
	v_pk_fma_f32 v[194:195], v[90:91], v[130:131], v[194:195]
	v_pk_fma_f32 v[192:193], v[88:89], v[128:129], v[192:193]
	s_add_u32 s38, s8, 0x1000
	s_addc_u32 s39, s9, 0
	global_store_dwordx4 v156, v[180:183], s[38:39] sc1
	global_store_dwordx4 v156, v[184:187], s[38:39] offset:64 sc1
	global_store_dwordx4 v156, v[188:191], s[38:39] offset:512 sc1
	global_store_dwordx4 v156, v[192:195], s[38:39] offset:576 sc1
	s_add_u32 s36, s0, 0x80000
	s_addc_u32 s37, s1, 0
	global_load_dwordx4 v[180:183], v156, s[36:37]
	global_load_dwordx4 v[184:187], v156, s[36:37] offset:64
	global_load_dwordx4 v[188:191], v156, s[36:37] offset:512
	global_load_dwordx4 v[192:195], v156, s[36:37] offset:576
	s_waitcnt vmcnt(16)
	v_pk_fma_f32 v[198:199], v[98:99], v[142:143], v[198:199]
	v_pk_fma_f32 v[196:197], v[96:97], v[140:141], v[196:197]
	v_pk_fma_f32 v[206:207], v[94:95], v[138:139], v[206:207]
	v_pk_fma_f32 v[204:205], v[92:93], v[136:137], v[204:205]
	v_pk_fma_f32 v[210:211], v[86:87], v[134:135], v[210:211]
	v_pk_fma_f32 v[208:209], v[84:85], v[132:133], v[208:209]
	v_pk_fma_f32 v[214:215], v[74:75], v[130:131], v[214:215]
	v_pk_fma_f32 v[212:213], v[72:73], v[128:129], v[212:213]
	s_add_u32 s38, s8, 0x2000
	s_addc_u32 s39, s9, 0
	global_store_dwordx4 v156, v[196:199], s[38:39] sc1
	global_store_dwordx4 v156, v[204:207], s[38:39] offset:64 sc1
	global_store_dwordx4 v156, v[208:211], s[38:39] offset:512 sc1
	global_store_dwordx4 v156, v[212:215], s[38:39] offset:576 sc1
	s_add_u32 s36, s0, 0x81000
	s_addc_u32 s37, s1, 0
	global_load_dwordx4 v[196:199], v156, s[36:37]
	global_load_dwordx4 v[204:207], v156, s[36:37] offset:64
	global_load_dwordx4 v[208:211], v156, s[36:37] offset:512
	global_load_dwordx4 v[212:215], v156, s[36:37] offset:576
	s_waitcnt vmcnt(16)
;     __device__ __forceinline__ void operator()(const f32x4 (&acc)[2][2][4][2], const pg8::Unit& u, int wr, int wc, int fr, int fq) const {
;     ...
; #pragma unroll
;                 for (int bj = 0; bj < 2; ++bj)
; #pragma unroll
;                     for (int n = 0; n < 2; ++n) {
;                         const f32x4 xv = *(const f32x4*)(xin + off + bj * 128 + n * 16);
;                         *(f32x4*)(out + off + bj * 128 + n * 16) = xv + gv[bj][n] * acc[ai][bj][m][n];
;                     }
;                 if (m == 3) asm volatile("" ::: "memory");
	v_pk_fma_f32 v[166:167], v[82:83], v[142:143], v[166:167]
	v_pk_fma_f32 v[164:165], v[80:81], v[140:141], v[164:165]
	v_pk_fma_f32 v[170:171], v[78:79], v[138:139], v[170:171]
	v_pk_fma_f32 v[168:169], v[76:77], v[136:137], v[168:169]
	v_pk_fma_f32 v[174:175], v[70:71], v[134:135], v[174:175]
	v_pk_fma_f32 v[172:173], v[68:69], v[132:133], v[172:173]
	v_pk_fma_f32 v[178:179], v[66:67], v[130:131], v[178:179]
	v_pk_fma_f32 v[176:177], v[64:65], v[128:129], v[176:177]
	s_add_u32 s38, s8, 0x3000
	s_addc_u32 s39, s9, 0
	global_store_dwordx4 v156, v[164:167], s[38:39] sc1
	global_store_dwordx4 v156, v[168:171], s[38:39] offset:64 sc1
	global_store_dwordx4 v156, v[172:175], s[38:39] offset:512 sc1
	global_store_dwordx4 v156, v[176:179], s[38:39] offset:576 sc1
	s_add_u32 s36, s0, 0x82000
	s_addc_u32 s37, s1, 0
	global_load_dwordx4 v[164:167], v156, s[36:37]
	global_load_dwordx4 v[168:171], v156, s[36:37] offset:64
	global_load_dwordx4 v[172:175], v156, s[36:37] offset:512
	global_load_dwordx4 v[176:179], v156, s[36:37] offset:576
	s_waitcnt vmcnt(16)
	v_pk_fma_f32 v[182:183], v[62:63], v[142:143], v[182:183]
	v_pk_fma_f32 v[180:181], v[60:61], v[140:141], v[180:181]
	v_pk_fma_f32 v[186:187], v[58:59], v[138:139], v[186:187]
	v_pk_fma_f32 v[184:185], v[56:57], v[136:137], v[184:185]
	v_pk_fma_f32 v[190:191], v[54:55], v[134:135], v[190:191]
	v_pk_fma_f32 v[188:189], v[52:53], v[132:133], v[188:189]
	v_pk_fma_f32 v[194:195], v[42:43], v[130:131], v[194:195]
	v_pk_fma_f32 v[192:193], v[40:41], v[128:129], v[192:193]
	s_add_u32 s38, s8, 0x80000
	s_addc_u32 s39, s9, 0
	global_store_dwordx4 v156, v[180:183], s[38:39] sc1
	global_store_dwordx4 v156, v[184:187], s[38:39] offset:64 sc1
	global_store_dwordx4 v156, v[188:191], s[38:39] offset:512 sc1
	global_store_dwordx4 v156, v[192:195], s[38:39] offset:576 sc1
	s_add_u32 s36, s0, 0x83000
	s_addc_u32 s37, s1, 0
	global_load_dwordx4 v[180:183], v156, s[36:37]
	global_load_dwordx4 v[184:187], v156, s[36:37] offset:64
	global_load_dwordx4 v[188:191], v156, s[36:37] offset:512
	global_load_dwordx4 v[192:195], v156, s[36:37] offset:576
	s_waitcnt vmcnt(16)
	v_pk_fma_f32 v[198:199], v[50:51], v[142:143], v[198:199]
	v_pk_fma_f32 v[196:197], v[48:49], v[140:141], v[196:197]
	v_pk_fma_f32 v[206:207], v[46:47], v[138:139], v[206:207]
	v_pk_fma_f32 v[204:205], v[44:45], v[136:137], v[204:205]
	v_pk_fma_f32 v[210:211], v[38:39], v[134:135], v[210:211]
	v_pk_fma_f32 v[208:209], v[36:37], v[132:133], v[208:209]
	v_pk_fma_f32 v[214:215], v[26:27], v[130:131], v[214:215]
	v_pk_fma_f32 v[212:213], v[24:25], v[128:129], v[212:213]
	s_add_u32 s38, s8, 0x81000
	s_addc_u32 s39, s9, 0
	global_store_dwordx4 v156, v[196:199], s[38:39] sc1
	global_store_dwordx4 v156, v[204:207], s[38:39] offset:64 sc1
	global_store_dwordx4 v156, v[208:211], s[38:39] offset:512 sc1
	global_store_dwordx4 v156, v[212:215], s[38:39] offset:576 sc1
	s_waitcnt vmcnt(12)
	v_pk_fma_f32 v[166:167], v[34:35], v[142:143], v[166:167]
	v_pk_fma_f32 v[164:165], v[32:33], v[140:141], v[164:165]
	v_pk_fma_f32 v[170:171], v[30:31], v[138:139], v[170:171]
	v_pk_fma_f32 v[168:169], v[28:29], v[136:137], v[168:169]
	v_pk_fma_f32 v[174:175], v[22:23], v[134:135], v[174:175]
	v_pk_fma_f32 v[172:173], v[20:21], v[132:133], v[172:173]
	v_pk_fma_f32 v[178:179], v[10:11], v[130:131], v[178:179]
	v_pk_fma_f32 v[176:177], v[8:9], v[128:129], v[176:177]
	s_add_u32 s38, s8, 0x82000
	s_addc_u32 s39, s9, 0
	global_store_dwordx4 v156, v[164:167], s[38:39] sc1
	global_store_dwordx4 v156, v[168:171], s[38:39] offset:64 sc1
	global_store_dwordx4 v156, v[172:175], s[38:39] offset:512 sc1
	global_store_dwordx4 v156, v[176:179], s[38:39] offset:576 sc1
	s_waitcnt vmcnt(8)
	v_pk_fma_f32 v[182:183], v[18:19], v[142:143], v[182:183]
	v_pk_fma_f32 v[180:181], v[16:17], v[140:141], v[180:181]
	v_pk_fma_f32 v[186:187], v[14:15], v[138:139], v[186:187]
	v_pk_fma_f32 v[184:185], v[12:13], v[136:137], v[184:185]
	v_pk_fma_f32 v[190:191], v[6:7], v[134:135], v[190:191]
	v_pk_fma_f32 v[188:189], v[4:5], v[132:133], v[188:189]
	v_pk_fma_f32 v[194:195], v[2:3], v[130:131], v[194:195]
	v_pk_fma_f32 v[192:193], v[0:1], v[128:129], v[192:193]
	s_add_u32 s38, s8, 0x83000
	s_addc_u32 s39, s9, 0
	global_store_dwordx4 v156, v[180:183], s[38:39] sc1
	global_store_dwordx4 v156, v[184:187], s[38:39] offset:64 sc1
	global_store_dwordx4 v156, v[188:191], s[38:39] offset:512 sc1
	global_store_dwordx4 v156, v[192:195], s[38:39] offset:576 sc1
	s_cbranch_vccnz .LBB0_571
	s_andn2_b64 vcc, exec, s[6:7]
	s_cbranch_vccnz .LBB0_570
	s_barrier
	s_branch .LBB0_570

;     __device__ __forceinline__ void operator()(const f32x4 (&acc)[2][2][4][2], const pg8::Unit& u, int wr, int wc, int fr, int fq) const {
;     ...
;         const float* gp = gatev + (size_t)(u.pm >> 3) * 3072 + col0;
;         f32x4 gv[2][2];
; #pragma unroll
;         for (int bj = 0; bj < 2; ++bj)
; #pragma unroll
;             for (int n = 0; n < 2; ++n) gv[bj][n] = *(const f32x4*)(gp + bj * 128 + n * 16);
; #pragma unroll
;         for (int ai = 0; ai < 2; ++ai)
; #pragma unroll
;             for (int m = 0; m < 4; ++m) {
;                 const size_t off = (size_t)(row0 + ai * 128 + m * 16) * DM + col0;
; #pragma unroll
;                 for (int bj = 0; bj < 2; ++bj)
; #pragma unroll
;                     for (int n = 0; n < 2; ++n) {
;                         const f32x4 xv = *(const f32x4*)(xin + off + bj * 128 + n * 16);
;                         *(f32x4*)(out + off + bj * 128 + n * 16) = xv + gv[bj][n] * acc[ai][bj][m][n];
;                     }
;                 if (m == 3) asm volatile("" ::: "memory");
;             }
.LBB0_1107:
	s_ashr_i32 s21, s28, 3
	v_lshl_or_b32 v128, s58, 8, v160
	s_mul_hi_i32 s23, s21, 0x3000
	s_mulk_i32 s21, 0x3000
	v_lshl_add_u32 v216, s28, 8, v158
	s_add_u32 s30, s47, s21
	v_ashrrev_i32_e32 v129, 31, v128
	s_addc_u32 s31, s48, s23
	v_lshlrev_b64 v[200:201], 2, v[128:129]
	v_lshl_add_u64 v[136:137], s[30:31], 0, v[200:201]
	v_and_b32_e32 v165, 0xffffff00, v216
	v_and_b32_e32 v166, 15, v216
	v_lshl_add_u32 v165, v166, 3, v165
	v_bfe_u32 v166, v216, 6, 1
	v_lshl_add_u32 v165, v166, 2, v165
	v_lshlrev_b32_e32 v156, 12, v165
	v_add_u32_e32 v156, v156, v200
	global_load_dwordx4 v[132:135], v[136:137], off
	global_load_dwordx4 v[128:131], v[136:137], off offset:64
	global_load_dwordx4 v[140:143], v[136:137], off offset:512
	s_nop 0
	global_load_dwordx4 v[136:139], v[136:137], off offset:576
	s_andn2_b64 vcc, exec, s[0:1]
	s_mov_b64 s[0:1], -1
	s_mov_b64 s[34:35], s[4:5]
	global_load_dwordx4 v[164:167], v156, s[34:35]
	global_load_dwordx4 v[168:171], v156, s[34:35] offset:64
	global_load_dwordx4 v[172:175], v156, s[34:35] offset:512
	global_load_dwordx4 v[176:179], v156, s[34:35] offset:576
	s_add_u32 s34, s4, 0x1000
	s_addc_u32 s35, s5, 0
	global_load_dwordx4 v[180:183], v156, s[34:35]
	global_load_dwordx4 v[184:187], v156, s[34:35] offset:64
	global_load_dwordx4 v[188:191], v156, s[34:35] offset:512
	global_load_dwordx4 v[192:195], v156, s[34:35] offset:576
	s_add_u32 s34, s4, 0x2000
	s_addc_u32 s35, s5, 0
	global_load_dwordx4 v[196:199], v156, s[34:35]
	global_load_dwordx4 v[204:207], v156, s[34:35] offset:64
	global_load_dwordx4 v[208:211], v156, s[34:35] offset:512
	global_load_dwordx4 v[212:215], v156, s[34:35] offset:576
	s_waitcnt vmcnt(8)
	v_pk_fma_f32 v[166:167], v[126:127], v[134:135], v[166:167]
	v_pk_fma_f32 v[164:165], v[124:125], v[132:133], v[164:165]
	v_pk_fma_f32 v[170:171], v[122:123], v[130:131], v[170:171]
	v_pk_fma_f32 v[168:169], v[120:121], v[128:129], v[168:169]
	v_pk_fma_f32 v[174:175], v[106:107], v[142:143], v[174:175]
	v_pk_fma_f32 v[172:173], v[104:105], v[140:141], v[172:173]
	v_pk_fma_f32 v[178:179], v[98:99], v[138:139], v[178:179]
	v_pk_fma_f32 v[176:177], v[96:97], v[136:137], v[176:177]
	s_mov_b64 s[36:37], s[4:5]
	global_store_dwordx4 v156, v[164:167], s[36:37] sc1
	global_store_dwordx4 v156, v[168:171], s[36:37] offset:64 sc1
	global_store_dwordx4 v156, v[172:175], s[36:37] offset:512 sc1
	global_store_dwordx4 v156, v[176:179], s[36:37] offset:576 sc1
	s_add_u32 s34, s4, 0x3000
	s_addc_u32 s35, s5, 0
	global_load_dwordx4 v[164:167], v156, s[34:35]
	global_load_dwordx4 v[168:171], v156, s[34:35] offset:64
	global_load_dwordx4 v[172:175], v156, s[34:35] offset:512
	global_load_dwordx4 v[176:179], v156, s[34:35] offset:576
	s_waitcnt vmcnt(12)
	v_pk_fma_f32 v[182:183], v[118:119], v[134:135], v[182:183]
	v_pk_fma_f32 v[180:181], v[116:117], v[132:133], v[180:181]
	v_pk_fma_f32 v[186:187], v[114:115], v[130:131], v[186:187]
	v_pk_fma_f32 v[184:185], v[112:113], v[128:129], v[184:185]
	v_pk_fma_f32 v[190:191], v[90:91], v[142:143], v[190:191]
	v_pk_fma_f32 v[188:189], v[88:89], v[140:141], v[188:189]
	v_pk_fma_f32 v[194:195], v[86:87], v[138:139], v[194:195]
	v_pk_fma_f32 v[192:193], v[84:85], v[136:137], v[192:193]
	s_add_u32 s36, s4, 0x1000
	s_addc_u32 s37, s5, 0
	global_store_dwordx4 v156, v[180:183], s[36:37] sc1
	global_store_dwordx4 v156, v[184:187], s[36:37] offset:64 sc1
	global_store_dwordx4 v156, v[188:191], s[36:37] offset:512 sc1
	global_store_dwordx4 v156, v[192:195], s[36:37] offset:576 sc1
	s_add_u32 s34, s4, 0x80000
	s_addc_u32 s35, s5, 0
	global_load_dwordx4 v[180:183], v156, s[34:35]
	global_load_dwordx4 v[184:187], v156, s[34:35] offset:64
	global_load_dwordx4 v[188:191], v156, s[34:35] offset:512
	global_load_dwordx4 v[192:195], v156, s[34:35] offset:576
	s_waitcnt vmcnt(16)
	v_pk_fma_f32 v[198:199], v[110:111], v[134:135], v[198:199]
	v_pk_fma_f32 v[196:197], v[108:109], v[132:133], v[196:197]
	v_pk_fma_f32 v[206:207], v[102:103], v[130:131], v[206:207]
	v_pk_fma_f32 v[204:205], v[100:101], v[128:129], v[204:205]
	v_pk_fma_f32 v[210:211], v[78:79], v[142:143], v[210:211]
	v_pk_fma_f32 v[208:209], v[76:77], v[140:141], v[208:209]
	v_pk_fma_f32 v[214:215], v[74:75], v[138:139], v[214:215]
	v_pk_fma_f32 v[212:213], v[72:73], v[136:137], v[212:213]
	s_add_u32 s36, s4, 0x2000
	s_addc_u32 s37, s5, 0
	global_store_dwordx4 v156, v[196:199], s[36:37] sc1
	global_store_dwordx4 v156, v[204:207], s[36:37] offset:64 sc1
	global_store_dwordx4 v156, v[208:211], s[36:37] offset:512 sc1
	global_store_dwordx4 v156, v[212:215], s[36:37] offset:576 sc1
	s_add_u32 s34, s4, 0x81000
	s_addc_u32 s35, s5, 0
	global_load_dwordx4 v[196:199], v156, s[34:35]
	global_load_dwordx4 v[204:207], v156, s[34:35] offset:64
	global_load_dwordx4 v[208:211], v156, s[34:35] offset:512
	global_load_dwordx4 v[212:215], v156, s[34:35] offset:576
	s_waitcnt vmcnt(16)
;     __device__ __forceinline__ void operator()(const f32x4 (&acc)[2][2][4][2], const pg8::Unit& u, int wr, int wc, int fr, int fq) const {
;     ...
; #pragma unroll
;                 for (int bj = 0; bj < 2; ++bj)
; #pragma unroll
;                     for (int n = 0; n < 2; ++n) {
;                         const f32x4 xv = *(const f32x4*)(xin + off + bj * 128 + n * 16);
;                         *(f32x4*)(out + off + bj * 128 + n * 16) = xv + gv[bj][n] * acc[ai][bj][m][n];
;                     }
;                 if (m == 3) asm volatile("" ::: "memory");
	v_pk_fma_f32 v[166:167], v[94:95], v[134:135], v[166:167]
	v_pk_fma_f32 v[164:165], v[92:93], v[132:133], v[164:165]
	v_pk_fma_f32 v[170:171], v[82:83], v[130:131], v[170:171]
	v_pk_fma_f32 v[168:169], v[80:81], v[128:129], v[168:169]
	v_pk_fma_f32 v[174:175], v[70:71], v[142:143], v[174:175]
	v_pk_fma_f32 v[172:173], v[68:69], v[140:141], v[172:173]
	v_pk_fma_f32 v[178:179], v[66:67], v[138:139], v[178:179]
	v_pk_fma_f32 v[176:177], v[64:65], v[136:137], v[176:177]
	s_add_u32 s36, s4, 0x3000
	s_addc_u32 s37, s5, 0
	global_store_dwordx4 v156, v[164:167], s[36:37] sc1
	global_store_dwordx4 v156, v[168:171], s[36:37] offset:64 sc1
	global_store_dwordx4 v156, v[172:175], s[36:37] offset:512 sc1
	global_store_dwordx4 v156, v[176:179], s[36:37] offset:576 sc1
	s_add_u32 s34, s4, 0x82000
	s_addc_u32 s35, s5, 0
	global_load_dwordx4 v[164:167], v156, s[34:35]
	global_load_dwordx4 v[168:171], v156, s[34:35] offset:64
	global_load_dwordx4 v[172:175], v156, s[34:35] offset:512
	global_load_dwordx4 v[176:179], v156, s[34:35] offset:576
	s_waitcnt vmcnt(16)
	v_pk_fma_f32 v[182:183], v[62:63], v[134:135], v[182:183]
	v_pk_fma_f32 v[180:181], v[60:61], v[132:133], v[180:181]
	v_pk_fma_f32 v[186:187], v[58:59], v[130:131], v[186:187]
	v_pk_fma_f32 v[184:185], v[56:57], v[128:129], v[184:185]
	v_pk_fma_f32 v[190:191], v[42:43], v[142:143], v[190:191]
	v_pk_fma_f32 v[188:189], v[40:41], v[140:141], v[188:189]
	v_pk_fma_f32 v[194:195], v[34:35], v[138:139], v[194:195]
	v_pk_fma_f32 v[192:193], v[32:33], v[136:137], v[192:193]
	s_add_u32 s36, s4, 0x80000
	s_addc_u32 s37, s5, 0
	global_store_dwordx4 v156, v[180:183], s[36:37] sc1
	global_store_dwordx4 v156, v[184:187], s[36:37] offset:64 sc1
	global_store_dwordx4 v156, v[188:191], s[36:37] offset:512 sc1
	global_store_dwordx4 v156, v[192:195], s[36:37] offset:576 sc1
	s_add_u32 s34, s4, 0x83000
	s_addc_u32 s35, s5, 0
	global_load_dwordx4 v[180:183], v156, s[34:35]
	global_load_dwordx4 v[184:187], v156, s[34:35] offset:64
	global_load_dwordx4 v[188:191], v156, s[34:35] offset:512
	global_load_dwordx4 v[192:195], v156, s[34:35] offset:576
	s_waitcnt vmcnt(16)
	v_pk_fma_f32 v[198:199], v[54:55], v[134:135], v[198:199]
	v_pk_fma_f32 v[196:197], v[52:53], v[132:133], v[196:197]
	v_pk_fma_f32 v[206:207], v[50:51], v[130:131], v[206:207]
	v_pk_fma_f32 v[204:205], v[48:49], v[128:129], v[204:205]
	v_pk_fma_f32 v[210:211], v[30:31], v[142:143], v[210:211]
	v_pk_fma_f32 v[208:209], v[28:29], v[140:141], v[208:209]
	v_pk_fma_f32 v[214:215], v[26:27], v[138:139], v[214:215]
	v_pk_fma_f32 v[212:213], v[24:25], v[136:137], v[212:213]
	s_add_u32 s36, s4, 0x81000
	s_addc_u32 s37, s5, 0
	global_store_dwordx4 v156, v[196:199], s[36:37] sc1
	global_store_dwordx4 v156, v[204:207], s[36:37] offset:64 sc1
	global_store_dwordx4 v156, v[208:211], s[36:37] offset:512 sc1
	global_store_dwordx4 v156, v[212:215], s[36:37] offset:576 sc1
	s_waitcnt vmcnt(12)
	v_pk_fma_f32 v[166:167], v[46:47], v[134:135], v[166:167]
	v_pk_fma_f32 v[164:165], v[44:45], v[132:133], v[164:165]
	v_pk_fma_f32 v[170:171], v[38:39], v[130:131], v[170:171]
	v_pk_fma_f32 v[168:169], v[36:37], v[128:129], v[168:169]
	v_pk_fma_f32 v[174:175], v[14:15], v[142:143], v[174:175]
	v_pk_fma_f32 v[172:173], v[12:13], v[140:141], v[172:173]
	v_pk_fma_f32 v[178:179], v[10:11], v[138:139], v[178:179]
	v_pk_fma_f32 v[176:177], v[8:9], v[136:137], v[176:177]
	s_add_u32 s36, s4, 0x82000
	s_addc_u32 s37, s5, 0
	global_store_dwordx4 v156, v[164:167], s[36:37] sc1
	global_store_dwordx4 v156, v[168:171], s[36:37] offset:64 sc1
	global_store_dwordx4 v156, v[172:175], s[36:37] offset:512 sc1
	global_store_dwordx4 v156, v[176:179], s[36:37] offset:576 sc1
	s_waitcnt vmcnt(8)
	v_pk_fma_f32 v[182:183], v[22:23], v[134:135], v[182:183]
	v_pk_fma_f32 v[180:181], v[20:21], v[132:133], v[180:181]
	v_pk_fma_f32 v[186:187], v[18:19], v[130:131], v[186:187]
	v_pk_fma_f32 v[184:185], v[16:17], v[128:129], v[184:185]
	v_pk_fma_f32 v[190:191], v[6:7], v[142:143], v[190:191]
	v_pk_fma_f32 v[188:189], v[4:5], v[140:141], v[188:189]
	v_pk_fma_f32 v[194:195], v[2:3], v[138:139], v[194:195]
	v_pk_fma_f32 v[192:193], v[0:1], v[136:137], v[192:193]
	s_add_u32 s36, s4, 0x83000
	s_addc_u32 s37, s5, 0
	global_store_dwordx4 v156, v[180:183], s[36:37] sc1
	global_store_dwordx4 v156, v[184:187], s[36:37] offset:64 sc1
	global_store_dwordx4 v156, v[188:191], s[36:37] offset:512 sc1
	global_store_dwordx4 v156, v[192:195], s[36:37] offset:576 sc1
	s_cbranch_vccnz .LBB0_1096
	s_andn2_b64 vcc, exec, s[8:9]
	s_cbranch_vccnz .LBB0_1095
	s_barrier
	s_branch .LBB0_1095
